# window attention: bias table loaded once per workgroup, Q-load wait merged into the first tile barrier wait
# speedup vs baseline: 1.0013x; 1.0013x over previous
; template <int MODE>
; __device__ __forceinline__ void attn_unit(const Tensors& T0, int ureq, int b, int hh, int qblk, LAS3 char* shm, const bool dummy = false) {
;     ...
;   { const float* gt = T.gtab + (MODE ? (16 + hh) : hh * 4) * TABW; for (int i = tid; i < (MODE ? 1 : 4) * TABW; i += 512) tab[i] = gt[i]; }
; __global__ void __launch_bounds__(NWAVES * 64, 2) mixer_fwd(Args args) {
;     ...
;         for (int U = vcu; U < 4096; U += G) {
;             int u = (U & 255) * 16 + (U >> 8), ureq, b, kvh, qb;
;             if (u < 2048) { ureq = 0; b = u >> 8; kvh = (u >> 6) & 3; qb = u & 63; }
;             else { u -= 2048; ureq = 1; b = u >> 9; kvh = (u >> 7) & 3; qb = u & 127; }
.LBB0_153:
	s_lshr_b32 s39, s19, s10
	v_mov_b32_e32 v16, v181
	s_mov_b64 s[44:45], s[24:25]
	s_mov_b64 s[40:41], s[16:17]
	s_mov_b64 s[42:43], s[26:27]
	s_mov_b64 s[10:11], s[20:21]
	s_mov_b64 s[40:41], s[22:23]
	s_mov_b64 s[46:47], s[34:35]
	s_mov_b64 s[48:49], s[64:65]
	s_mov_b64 s[50:51], s[52:53]
	v_readfirstlane_b32 s81, v16
	v_cmp_gt_i32_e32 vcc, s76, v16
	s_and_saveexec_b64 s[46:47], vcc
	s_cbranch_execz .LBB0_156
	s_cmpk_gt_i32 s33, 0xff
	s_cbranch_scc1 .LBB0_156
	s_and_b32 s50, s39, 3
	s_mulk_i32 s50, 0x2400
	s_add_u32 s48, s48, s50
	v_ashrrev_i32_e32 v17, 31, v16
	s_addc_u32 s49, s49, 0
	v_add_u32_e32 v0, 0xfffffe00, v16
	v_lshl_add_u32 v4, v16, 2, s57
	v_lshl_add_u64 v[2:3], v[16:17], 2, s[48:49]
	s_mov_b64 s[48:49], 0

; #define ATT_BAR_V(full) do { if (full) { if (MODE) ATT_WAIT_BAR(4); else ATT_WAIT_BAR(2); } else ATT_WAIT_BAR(0); } while (0)
; #define ATT_BAR_L() asm volatile("s_waitcnt lgkmcnt(0)\n\ts_barrier" ::: "memory")
; template <int MODE>
; __device__ __forceinline__ void attn_unit(const Tensors& T0, int ureq, int b, int hh, int qblk, LAS3 char* shm, const bool dummy = false) {
;     ...
;   bf16x8 qr[4];
; #pragma unroll
;   for (int d0 = 0; d0 < 4; ++d0) qr[d0] = *reinterpret_cast<const bf16x8*>(&Qw[(long)r32 * PQ + d0 * 16 + hi * 8]);
;   asm volatile("s_waitcnt vmcnt(0)" ::: "memory");
;   const int drow = 8 * wid + (lane >> 3);
;   const bf16_t* ksrc = Kh + (long)drow * PK + (((lane & 7) ^ ((drow >> 1) & 7)) * 8);
;   const bf16_t* vsrc = Vh + (long)drow * PK + ((((lane >> 2) & 1) ^ ((lane >> 4) & 1)) * 32) + (lane & 3) * 8;
;   const unsigned dwv = lds0 + wid * 1024;
;     ...
;   int t_lo = 0, t_hi = S / 64;
;   if (!MODE) { t_lo = (Q0 >= 128 ? Q0 - 128 : 0) / 64; const int e = Q0 + 64 + 128; t_hi = (e < S ? e : S) / 64; }
;   const int NT = t_hi - t_lo;
;   const int grp = wid >> 2;
;   lds_cptr kp[4];
; #pragma unroll
;   for (int d0 = 0; d0 < 4; ++d0) kp[d0] = (lds_cptr)shm + (MODE ? sub * OFF_K2 : 0) + r32 * 128 + (((2 * d0 + hi) ^ ((r32 >> 1) & 7)) << 4);
;   const int vrow = 4 * hi + ((lane & 15) >> 2), vsw = (lane >> 3) & 1;
;   const lds_cptr vpe = (lds_cptr)shm + OFF_V + vrow * 128 + vsw * 64 + ((lane >> 4) & 1) * 32 + (lane & 3) * 8;
;   const lds_cptr vpo = (lds_cptr)shm + OFF_V + vrow * 128 + (vsw ^ 1) * 64 + ((lane >> 4) & 1) * 32 + (lane & 3) * 8;
;   float mhat, l_reg, curcb; bool first; f32x16 o[ND]; f32x16 negm; u32x4 pw[4];
;     ...
;   bf16x8 vA[ND], vB[ND];
;   mhat = MODE ? 0.f : sinkv; l_reg = (!MODE && hi == 0) ? 1.f : 0.f; curcb = 0.f; first = MODE ? true : false;
; #pragma unroll
;   for (int d = 0; d < ND; ++d) o[d] = f32x16{};
; #pragma unroll
;   for (int r = 0; r < 16; ++r) negm[r] = -mhat;
; #pragma unroll
;   for (int j = 0; j < 4; ++j) pw[j] = (u32x4){0u, 0u, 0u, 0u};
;   if (!(ATT_ABL == 2 && dummy)) { ATT_DMA(t_lo, 0); ATT_DMA(t_lo + 1, SLOTB); }
;   ATT_BAR_V(true);
;   if (grp == 1) { if (NT > 2 && !(ATT_ABL == 2 && dummy)) ATT_DMA(t_lo + 2, 2 * SLOTB); ATT_BAR_L(); }
.LBB0_156:
	s_or_b64 exec, exec, s[46:47]
	s_and_b32 s82, s19, s37
	s_and_b32 s19, s39, 3
	s_ashr_i32 s39, s38, 31
	s_ashr_i32 s37, s81, 6
	s_lshl_b64 s[46:47], s[38:39], 13
	s_add_u32 s46, s46, 0x8000
	s_addc_u32 s47, s47, 0
	s_lshl_b64 s[38:39], s[38:39], 12
	s_and_b64 s[4:5], s[4:5], exec
	s_cselect_b32 s5, s39, s47
	s_cselect_b32 s4, s38, s46
	s_lshl_b32 s38, s37, 5
	s_lshl_b32 s46, s82, 6
	s_and_b32 s38, s38, 32
	s_ashr_i32 s84, s81, 7
	s_or_b32 s85, s38, s46
	s_add_u32 s54, s4, s85
	s_addc_u32 s55, s5, 0
	s_lshl_b64 s[38:39], s[54:55], 11
	s_add_u32 s47, s44, s38
	s_addc_u32 s39, s45, s39
	s_lshl_b32 s38, s19, 2
	s_add_i32 s38, s84, s38
	s_lshl_b32 s44, s38, 6
	s_ashr_i32 s45, s44, 31
	s_lshl_b64 s[66:67], s[44:45], 1
	s_add_u32 s44, s47, s66
	s_addc_u32 s45, s39, s67
	s_lshl_b64 s[4:5], s[4:5], 10
	s_add_u32 s4, s42, s4
	s_addc_u32 s5, s43, s5
	s_lshl_b32 s19, s19, 7
	s_add_u32 s4, s4, s19
	s_addc_u32 s5, s5, 0
	s_ashr_i32 s39, s38, 31
	v_and_b32_e32 v123, 31, v16
	s_lshl_b64 s[38:39], s[38:39], 2
	v_bfe_u32 v122, v16, 5, 1
	s_add_u32 s38, s40, s38
	v_lshlrev_b32_e32 v0, 11, v123
	s_addc_u32 s39, s41, s39
	v_lshl_or_b32 v0, v122, 4, v0
	v_mov_b64_e32 v[2:3], s[38:39]
	v_lshl_add_u64 v[14:15], s[44:45], 0, v[0:1]
	flat_load_dword v17, v[2:3]
	s_nop 0
	flat_load_dwordx4 v[2:5], v[14:15]
	flat_load_dwordx4 v[6:9], v[14:15] offset:32
	flat_load_dwordx4 v[10:13], v[14:15] offset:64
	flat_load_dwordx4 v[96:99], v[14:15] offset:96
	v_bfe_u32 v18, v16, 3, 3
	v_lshl_or_b32 v14, s37, 3, v18
	v_ashrrev_i32_e32 v15, 31, v14
	v_lshlrev_b64 v[20:21], 10, v[14:15]
	v_lshrrev_b32_e32 v0, 1, v14
	v_lshl_add_u64 v[22:23], s[4:5], 0, v[20:21]
	v_xor_b32_e32 v0, v0, v16
	s_add_i32 s4, s46, 0xffffff80
	s_addk_i32 s46, 0xc0
	v_lshlrev_b32_e32 v0, 4, v0
	s_lshl_b32 s80, s37, 10
	s_min_u32 s5, s46, s18
	v_and_b32_e32 v0, 0x70, v0
	v_lshrrev_b32_e32 v21, 2, v16
	v_lshrrev_b32_e32 v20, 4, v16
	s_add_i32 s80, s80, 0
	s_ashr_i32 s4, s4, 6
	s_lshr_b32 s83, s5, 6
	v_lshl_add_u64 v[14:15], v[22:23], 0, v[0:1]
	v_xor_b32_e32 v0, v21, v20
	s_cmp_gt_u32 s82, 1
	v_lshlrev_b32_e32 v19, 3, v16
	v_lshlrev_b32_e32 v0, 6, v0
	s_cselect_b32 s68, s4, 0
	v_and_b32_e32 v19, 24, v19
	v_and_b32_e32 v0, 64, v0
	s_ashr_i32 s69, s68, 31
	v_lshl_add_u64 v[22:23], v[22:23], 0, v[0:1]
	v_lshlrev_b32_e32 v0, 1, v19
	s_lshl_b64 s[4:5], s[68:69], 16
	v_lshl_add_u64 v[120:121], v[22:23], 0, v[0:1]
	v_lshl_add_u64 v[22:23], v[14:15], 0, s[4:5]
	s_mov_b32 s18, m0
	s_mov_b32 m0, s80
	s_nop 0
	global_load_lds_dwordx4 v[22:23], off
	s_mov_b32 m0, s18
	s_sub_i32 s79, s83, s68
	s_add_i32 s18, s80, 0x4000
	v_lshl_add_u64 v[22:23], v[120:121], 0, s[4:5]
	s_add_u32 s4, s4, 0x10000
	v_lshl_add_u64 v[22:23], v[22:23], 0, s[8:9]
	s_addc_u32 s5, s5, 0
	s_mov_b32 s19, m0
	s_mov_b32 m0, s18
	s_nop 0
	global_load_lds_dwordx4 v[22:23], off
	s_mov_b32 m0, s19
	v_lshl_add_u64 v[22:23], v[14:15], 0, s[4:5]
	s_add_i32 s18, s80, 0x8000
	s_mov_b32 s19, m0
	s_mov_b32 m0, s18
	s_nop 0
	global_load_lds_dwordx4 v[22:23], off
	s_mov_b32 m0, s19
	v_lshl_add_u64 v[22:23], v[120:121], 0, s[4:5]
	s_add_i32 s4, s80, 0xc000
	v_lshl_add_u64 v[22:23], v[22:23], 0, s[8:9]
	s_mov_b32 s5, m0
	s_mov_b32 m0, s4
	s_nop 0
	global_load_lds_dwordx4 v[22:23], off
	s_mov_b32 m0, s5
	s_and_b32 s4, s81, 0xffffff00
	s_waitcnt vmcnt(2) lgkmcnt(0)
	s_barrier
	s_cmpk_eq_i32 s4, 0x100
	s_cselect_b64 s[70:71], -1, 0
	s_and_b64 vcc, exec, s[70:71]
	s_cbranch_vccz .LBB0_160
	s_cmp_lt_i32 s79, 3
	s_cbranch_scc1 .LBB0_159
	s_add_i32 s4, s68, 2
	s_mov_b32 s5, s36
	s_lshl_b64 s[4:5], s[4:5], 16
	v_lshl_add_u64 v[22:23], v[14:15], 0, s[4:5]
	s_add_i32 s18, s80, 0x10000
	s_mov_b32 s19, m0
	s_mov_b32 m0, s18
	s_nop 0
	global_load_lds_dwordx4 v[22:23], off
	s_mov_b32 m0, s19
	v_lshl_add_u64 v[22:23], v[120:121], 0, s[4:5]
	v_lshl_add_u64 v[22:23], v[22:23], 0, s[8:9]
	s_add_i32 s4, s80, 0x14000
	s_mov_b32 s5, m0
	s_mov_b32 m0, s4
	s_nop 0
	global_load_lds_dwordx4 v[22:23], off
	s_mov_b32 m0, s5
